# nt policy also on the P3 q and k/v output stores and the attention output stores (write streams consumed only in the next phase)
# speedup vs baseline: 1.0280x; 1.0047x over previous
.LBB0_581:
	v_lshl_or_b32 v144, s46, 8, v157
	v_lshl_add_u32 v164, s45, 8, v155
	v_mov_b64_e32 v[142:143], s[8:9]
	v_ashrrev_i32_e32 v145, 31, v144
	v_mad_i64_i32 v[162:163], s[18:19], v164, s42, v[142:143]
	v_lshlrev_b64 v[144:145], 1, v[144:145]
	v_lshl_add_u64 v[162:163], v[162:163], 0, v[144:145]
	v_cvt_pk_bf16_f32 v124, v124, v125
	v_cvt_pk_bf16_f32 v125, v126, v127
	v_cvt_pk_bf16_f32 v126, v120, v121
	v_cvt_pk_bf16_f32 v127, v122, v123
	global_store_dwordx4 v[162:163], v[124:127], off nt
	v_cvt_pk_bf16_f32 v112, v112, v113
	v_cvt_pk_bf16_f32 v113, v114, v115
	v_cvt_pk_bf16_f32 v114, v104, v105
	v_or_b32_e32 v104, 16, v164
	v_mad_i64_i32 v[104:105], s[18:19], v104, s42, v[142:143]
	v_cvt_pk_bf16_f32 v115, v106, v107
	global_store_dwordx4 v[162:163], v[112:115], off offset:256 nt
	s_and_b64 vcc, exec, s[0:1]
	s_mov_b64 s[0:1], -1
	v_lshl_add_u64 v[112:113], v[104:105], 0, v[144:145]
	v_cvt_pk_bf16_f32 v104, v116, v117
	v_cvt_pk_bf16_f32 v105, v118, v119
	v_cvt_pk_bf16_f32 v106, v108, v109
	v_cvt_pk_bf16_f32 v107, v110, v111
	global_store_dwordx4 v[112:113], v[104:107], off nt
	v_cvt_pk_bf16_f32 v96, v96, v97
	v_cvt_pk_bf16_f32 v97, v98, v99
	v_cvt_pk_bf16_f32 v98, v88, v89
	v_or_b32_e32 v88, 32, v164
	v_mad_i64_i32 v[88:89], s[18:19], v88, s42, v[142:143]
	v_cvt_pk_bf16_f32 v99, v90, v91
	global_store_dwordx4 v[112:113], v[96:99], off offset:256 nt
	s_nop 1
	v_lshl_add_u64 v[96:97], v[88:89], 0, v[144:145]
	v_cvt_pk_bf16_f32 v88, v100, v101
	v_cvt_pk_bf16_f32 v89, v102, v103
	v_cvt_pk_bf16_f32 v90, v92, v93
	v_cvt_pk_bf16_f32 v91, v94, v95
	global_store_dwordx4 v[96:97], v[88:91], off nt
	v_cvt_pk_bf16_f32 v80, v80, v81
	v_cvt_pk_bf16_f32 v81, v82, v83
	v_cvt_pk_bf16_f32 v82, v72, v73
	v_or_b32_e32 v72, 48, v164
	v_mad_i64_i32 v[72:73], s[18:19], v72, s42, v[142:143]
	v_cvt_pk_bf16_f32 v83, v74, v75
	global_store_dwordx4 v[96:97], v[80:83], off offset:256 nt
	s_nop 1
	v_lshl_add_u64 v[80:81], v[72:73], 0, v[144:145]
	v_cvt_pk_bf16_f32 v72, v84, v85
	v_cvt_pk_bf16_f32 v73, v86, v87
	v_cvt_pk_bf16_f32 v74, v76, v77
	v_cvt_pk_bf16_f32 v75, v78, v79
	global_store_dwordx4 v[80:81], v[72:75], off nt
	v_cvt_pk_bf16_f32 v68, v68, v69
	v_cvt_pk_bf16_f32 v69, v70, v71
	v_cvt_pk_bf16_f32 v70, v64, v65
	v_add_u32_e32 v64, 0x80, v164
	v_mad_i64_i32 v[64:65], s[18:19], v64, s42, v[142:143]
	v_lshl_add_u64 v[64:65], v[64:65], 0, v[144:145]
	v_cvt_pk_bf16_f32 v71, v66, v67
	global_store_dwordx4 v[80:81], v[68:71], off offset:256 nt
	v_cvt_pk_bf16_f32 v60, v60, v61
	v_cvt_pk_bf16_f32 v61, v62, v63
	v_cvt_pk_bf16_f32 v62, v56, v57
	v_cvt_pk_bf16_f32 v63, v58, v59
	global_store_dwordx4 v[64:65], v[60:63], off nt
	v_cvt_pk_bf16_f32 v48, v48, v49
	v_cvt_pk_bf16_f32 v49, v50, v51
	v_cvt_pk_bf16_f32 v50, v40, v41
	v_add_u32_e32 v40, 0x90, v164
	v_mad_i64_i32 v[40:41], s[18:19], v40, s42, v[142:143]
	v_cvt_pk_bf16_f32 v51, v42, v43
	global_store_dwordx4 v[64:65], v[48:51], off offset:256 nt
	s_nop 1
	v_lshl_add_u64 v[48:49], v[40:41], 0, v[144:145]
	v_cvt_pk_bf16_f32 v40, v52, v53
	v_cvt_pk_bf16_f32 v41, v54, v55
	v_cvt_pk_bf16_f32 v42, v44, v45
	v_cvt_pk_bf16_f32 v43, v46, v47
	global_store_dwordx4 v[48:49], v[40:43], off nt
	v_cvt_pk_bf16_f32 v32, v32, v33
	v_cvt_pk_bf16_f32 v33, v34, v35
	v_cvt_pk_bf16_f32 v34, v24, v25
	v_add_u32_e32 v24, 0xa0, v164
	v_mad_i64_i32 v[24:25], s[18:19], v24, s42, v[142:143]
	v_cvt_pk_bf16_f32 v35, v26, v27
	global_store_dwordx4 v[48:49], v[32:35], off offset:256 nt
	s_nop 1
	v_lshl_add_u64 v[32:33], v[24:25], 0, v[144:145]
	v_cvt_pk_bf16_f32 v24, v36, v37
	v_cvt_pk_bf16_f32 v25, v38, v39
	v_cvt_pk_bf16_f32 v26, v28, v29
	v_cvt_pk_bf16_f32 v27, v30, v31
	global_store_dwordx4 v[32:33], v[24:27], off nt
	v_cvt_pk_bf16_f32 v16, v16, v17
	v_cvt_pk_bf16_f32 v17, v18, v19
	v_cvt_pk_bf16_f32 v18, v8, v9
	v_add_u32_e32 v8, 0xb0, v164
	v_mad_i64_i32 v[8:9], s[18:19], v8, s42, v[142:143]
	v_cvt_pk_bf16_f32 v19, v10, v11
	global_store_dwordx4 v[32:33], v[16:19], off offset:256 nt
	s_nop 1
	v_lshl_add_u64 v[16:17], v[8:9], 0, v[144:145]
	v_cvt_pk_bf16_f32 v8, v20, v21
	v_cvt_pk_bf16_f32 v9, v22, v23
	v_cvt_pk_bf16_f32 v10, v12, v13
	v_cvt_pk_bf16_f32 v11, v14, v15
	global_store_dwordx4 v[16:17], v[8:11], off nt
	v_cvt_pk_bf16_f32 v4, v4, v5
	v_cvt_pk_bf16_f32 v5, v6, v7
	v_cvt_pk_bf16_f32 v6, v0, v1
	v_cvt_pk_bf16_f32 v7, v2, v3
	global_store_dwordx4 v[16:17], v[4:7], off offset:256 nt
	s_cbranch_vccnz .LBB0_565
	s_andn2_b64 vcc, exec, s[6:7]
	s_cbranch_vccnz .LBB0_564
	s_barrier
	s_branch .LBB0_564

.LBB0_615:
	v_cvt_pk_bf16_f32 v124, v124, v125
	v_cvt_pk_bf16_f32 v125, v126, v127
	v_cvt_pk_bf16_f32 v126, v120, v121
	v_cndmask_b32_e64 v120, 0, 1, s[30:31]
	v_cvt_pk_bf16_f32 v127, v122, v123
	s_mov_b64 s[34:35], -1
	v_cmp_ne_u32_e64 s[0:1], 1, v120
	s_andn2_b64 vcc, exec, s[30:31]
	v_add_u32_e32 v122, s21, v150
	global_store_dwordx4 v[148:149], v[124:127], off nt
	s_cbranch_vccnz .LBB0_617
	v_mov_b32_e32 v123, v137
	v_lshl_add_u64 v[120:121], v[122:123], 1, v[146:147]
	v_lshl_add_u64 v[124:125], v[120:121], 0, s[18:19]
	s_mov_b64 s[34:35], 0

.LBB0_619:
	v_cvt_pk_bf16_f32 v116, v116, v117
	v_cvt_pk_bf16_f32 v117, v118, v119
	v_cvt_pk_bf16_f32 v118, v112, v113
	v_cvt_pk_bf16_f32 v119, v114, v115
	v_or_b32_e32 v114, 16, v142
	v_ashrrev_i32_e32 v115, 31, v114
	v_lshlrev_b64 v[112:113], 10, v[114:115]
	s_mov_b64 s[30:31], -1
	s_and_b64 vcc, exec, s[0:1]
	v_lshl_add_u64 v[112:113], s[10:11], 0, v[112:113]
	global_store_dwordx4 v[124:125], v[116:119], off nt
	s_cbranch_vccnz .LBB0_621
	v_mov_b32_e32 v141, v137
	v_lshl_add_u64 v[116:117], v[140:141], 1, v[112:113]
	v_lshl_add_u64 v[116:117], v[116:117], 0, s[16:17]
	s_mov_b64 s[30:31], 0

.LBB0_623:
	s_and_b64 vcc, exec, s[0:1]
	s_mov_b64 s[30:31], -1
	v_cvt_pk_bf16_f32 v108, v108, v109
	v_cvt_pk_bf16_f32 v109, v110, v111
	v_cvt_pk_bf16_f32 v110, v104, v105
	v_cvt_pk_bf16_f32 v111, v106, v107
	global_store_dwordx4 v[116:117], v[108:111], off nt
	s_cbranch_vccnz .LBB0_625
	v_mov_b32_e32 v123, v137
	v_lshl_add_u64 v[104:105], v[122:123], 1, v[112:113]
	v_lshl_add_u64 v[104:105], v[104:105], 0, s[18:19]
	s_mov_b64 s[30:31], 0

.LBB0_627:
	v_cvt_pk_bf16_f32 v100, v100, v101
	v_cvt_pk_bf16_f32 v101, v102, v103
	v_cvt_pk_bf16_f32 v102, v96, v97
	v_cvt_pk_bf16_f32 v103, v98, v99
	v_or_b32_e32 v98, 32, v142
	v_ashrrev_i32_e32 v99, 31, v98
	v_lshlrev_b64 v[96:97], 10, v[98:99]
	s_mov_b64 s[30:31], -1
	s_and_b64 vcc, exec, s[0:1]
	v_lshl_add_u64 v[96:97], s[10:11], 0, v[96:97]
	global_store_dwordx4 v[104:105], v[100:103], off nt
	s_cbranch_vccnz .LBB0_629
	v_mov_b32_e32 v141, v137
	v_lshl_add_u64 v[100:101], v[140:141], 1, v[96:97]
	v_lshl_add_u64 v[100:101], v[100:101], 0, s[16:17]
	s_mov_b64 s[30:31], 0

.LBB0_631:
	s_and_b64 vcc, exec, s[0:1]
	s_mov_b64 s[30:31], -1
	v_cvt_pk_bf16_f32 v92, v92, v93
	v_cvt_pk_bf16_f32 v93, v94, v95
	v_cvt_pk_bf16_f32 v94, v88, v89
	v_cvt_pk_bf16_f32 v95, v90, v91
	global_store_dwordx4 v[100:101], v[92:95], off nt
	s_cbranch_vccnz .LBB0_633
	v_mov_b32_e32 v123, v137
	v_lshl_add_u64 v[88:89], v[122:123], 1, v[96:97]
	v_lshl_add_u64 v[88:89], v[88:89], 0, s[18:19]
	s_mov_b64 s[30:31], 0

.LBB0_635:
	v_cvt_pk_bf16_f32 v84, v84, v85
	v_cvt_pk_bf16_f32 v85, v86, v87
	v_cvt_pk_bf16_f32 v86, v80, v81
	v_cvt_pk_bf16_f32 v87, v82, v83
	v_or_b32_e32 v82, 48, v142
	v_ashrrev_i32_e32 v83, 31, v82
	v_lshlrev_b64 v[80:81], 10, v[82:83]
	s_mov_b64 s[30:31], -1
	s_and_b64 vcc, exec, s[0:1]
	v_lshl_add_u64 v[80:81], s[10:11], 0, v[80:81]
	global_store_dwordx4 v[88:89], v[84:87], off nt
	s_cbranch_vccnz .LBB0_637
	v_mov_b32_e32 v141, v137
	v_lshl_add_u64 v[84:85], v[140:141], 1, v[80:81]
	v_lshl_add_u64 v[84:85], v[84:85], 0, s[16:17]
	s_mov_b64 s[30:31], 0

.LBB0_639:
	s_and_b64 vcc, exec, s[0:1]
	s_mov_b64 s[30:31], -1
	v_cvt_pk_bf16_f32 v76, v76, v77
	v_cvt_pk_bf16_f32 v77, v78, v79
	v_cvt_pk_bf16_f32 v78, v72, v73
	v_cvt_pk_bf16_f32 v79, v74, v75
	global_store_dwordx4 v[84:85], v[76:79], off nt
	s_cbranch_vccnz .LBB0_641
	v_mov_b32_e32 v123, v137
	v_lshl_add_u64 v[72:73], v[122:123], 1, v[80:81]
	v_lshl_add_u64 v[72:73], v[72:73], 0, s[18:19]
	s_mov_b64 s[30:31], 0

.LBB0_643:
	v_cvt_pk_bf16_f32 v68, v68, v69
	v_cvt_pk_bf16_f32 v69, v70, v71
	v_cvt_pk_bf16_f32 v70, v64, v65
	v_cvt_pk_bf16_f32 v71, v66, v67
	v_add_u32_e32 v66, 0x80, v142
	v_ashrrev_i32_e32 v67, 31, v66
	v_lshlrev_b64 v[64:65], 10, v[66:67]
	s_mov_b64 s[30:31], -1
	s_and_b64 vcc, exec, s[0:1]
	v_lshl_add_u64 v[64:65], s[10:11], 0, v[64:65]
	global_store_dwordx4 v[72:73], v[68:71], off nt
	s_cbranch_vccnz .LBB0_645
	v_mov_b32_e32 v141, v137
	v_lshl_add_u64 v[68:69], v[140:141], 1, v[64:65]
	v_lshl_add_u64 v[68:69], v[68:69], 0, s[16:17]
	s_mov_b64 s[30:31], 0

.LBB0_647:
	s_and_b64 vcc, exec, s[0:1]
	s_mov_b64 s[30:31], -1
	v_cvt_pk_bf16_f32 v60, v60, v61
	v_cvt_pk_bf16_f32 v61, v62, v63
	v_cvt_pk_bf16_f32 v62, v56, v57
	v_cvt_pk_bf16_f32 v63, v58, v59
	global_store_dwordx4 v[68:69], v[60:63], off nt
	s_cbranch_vccnz .LBB0_649
	v_mov_b32_e32 v123, v137
	v_lshl_add_u64 v[56:57], v[122:123], 1, v[64:65]
	v_lshl_add_u64 v[56:57], v[56:57], 0, s[18:19]
	s_mov_b64 s[30:31], 0

.LBB0_651:
	v_cvt_pk_bf16_f32 v52, v52, v53
	v_cvt_pk_bf16_f32 v53, v54, v55
	v_cvt_pk_bf16_f32 v54, v48, v49
	v_cvt_pk_bf16_f32 v55, v50, v51
	v_add_u32_e32 v50, 0x90, v142
	v_ashrrev_i32_e32 v51, 31, v50
	v_lshlrev_b64 v[48:49], 10, v[50:51]
	s_mov_b64 s[30:31], -1
	s_and_b64 vcc, exec, s[0:1]
	v_lshl_add_u64 v[48:49], s[10:11], 0, v[48:49]
	global_store_dwordx4 v[56:57], v[52:55], off nt
	s_cbranch_vccnz .LBB0_653
	v_mov_b32_e32 v141, v137
	v_lshl_add_u64 v[52:53], v[140:141], 1, v[48:49]
	v_lshl_add_u64 v[52:53], v[52:53], 0, s[16:17]
	s_mov_b64 s[30:31], 0

.LBB0_655:
	s_and_b64 vcc, exec, s[0:1]
	s_mov_b64 s[30:31], -1
	v_cvt_pk_bf16_f32 v44, v44, v45
	v_cvt_pk_bf16_f32 v45, v46, v47
	v_cvt_pk_bf16_f32 v46, v40, v41
	v_cvt_pk_bf16_f32 v47, v42, v43
	global_store_dwordx4 v[52:53], v[44:47], off nt
	s_cbranch_vccnz .LBB0_657
	v_mov_b32_e32 v123, v137
	v_lshl_add_u64 v[40:41], v[122:123], 1, v[48:49]
	v_lshl_add_u64 v[40:41], v[40:41], 0, s[18:19]
	s_mov_b64 s[30:31], 0

.LBB0_659:
	v_cvt_pk_bf16_f32 v36, v36, v37
	v_cvt_pk_bf16_f32 v37, v38, v39
	v_cvt_pk_bf16_f32 v38, v32, v33
	v_cvt_pk_bf16_f32 v39, v34, v35
	v_add_u32_e32 v34, 0xa0, v142
	v_ashrrev_i32_e32 v35, 31, v34
	v_lshlrev_b64 v[32:33], 10, v[34:35]
	s_mov_b64 s[30:31], -1
	s_and_b64 vcc, exec, s[0:1]
	v_lshl_add_u64 v[32:33], s[10:11], 0, v[32:33]
	global_store_dwordx4 v[40:41], v[36:39], off nt
	s_cbranch_vccnz .LBB0_661
	v_mov_b32_e32 v141, v137
	v_lshl_add_u64 v[36:37], v[140:141], 1, v[32:33]
	v_lshl_add_u64 v[36:37], v[36:37], 0, s[16:17]
	s_mov_b64 s[30:31], 0

.LBB0_663:
	s_and_b64 vcc, exec, s[0:1]
	s_mov_b64 s[30:31], -1
	v_cvt_pk_bf16_f32 v28, v28, v29
	v_cvt_pk_bf16_f32 v29, v30, v31
	v_cvt_pk_bf16_f32 v30, v24, v25
	v_cvt_pk_bf16_f32 v31, v26, v27
	global_store_dwordx4 v[36:37], v[28:31], off nt
	s_cbranch_vccnz .LBB0_665
	v_mov_b32_e32 v123, v137
	v_lshl_add_u64 v[24:25], v[122:123], 1, v[32:33]
	v_lshl_add_u64 v[24:25], v[24:25], 0, s[18:19]
	s_mov_b64 s[30:31], 0

.LBB0_667:
	v_cvt_pk_bf16_f32 v20, v20, v21
	v_cvt_pk_bf16_f32 v21, v22, v23
	v_cvt_pk_bf16_f32 v22, v16, v17
	v_cvt_pk_bf16_f32 v23, v18, v19
	v_add_u32_e32 v18, 0xb0, v142
	v_ashrrev_i32_e32 v19, 31, v18
	v_lshlrev_b64 v[16:17], 10, v[18:19]
	s_mov_b64 s[30:31], -1
	s_and_b64 vcc, exec, s[0:1]
	v_lshl_add_u64 v[16:17], s[10:11], 0, v[16:17]
	global_store_dwordx4 v[24:25], v[20:23], off nt
	s_cbranch_vccnz .LBB0_669
	v_mov_b32_e32 v141, v137
	v_lshl_add_u64 v[20:21], v[140:141], 1, v[16:17]
	v_lshl_add_u64 v[20:21], v[20:21], 0, s[16:17]
	s_mov_b64 s[30:31], 0

.LBB0_671:
	s_and_b64 vcc, exec, s[0:1]
	s_mov_b64 s[0:1], -1
	v_cvt_pk_bf16_f32 v12, v12, v13
	v_cvt_pk_bf16_f32 v13, v14, v15
	v_cvt_pk_bf16_f32 v14, v8, v9
	v_cvt_pk_bf16_f32 v15, v10, v11
	global_store_dwordx4 v[20:21], v[12:15], off nt
	s_cbranch_vccnz .LBB0_673
	v_mov_b32_e32 v123, v137
	v_lshl_add_u64 v[8:9], v[122:123], 1, v[16:17]
	v_lshl_add_u64 v[8:9], v[8:9], 0, s[18:19]
	s_mov_b64 s[0:1], 0

.LBB0_675:
	s_andn2_b64 vcc, exec, s[24:25]
	s_mov_b64 s[0:1], -1
	v_cvt_pk_bf16_f32 v4, v4, v5
	v_cvt_pk_bf16_f32 v5, v6, v7
	v_cvt_pk_bf16_f32 v6, v0, v1
	v_cvt_pk_bf16_f32 v7, v2, v3
	global_store_dwordx4 v[8:9], v[4:7], off nt
	s_cbranch_vccnz .LBB0_598
	s_andn2_b64 vcc, exec, s[6:7]
	s_cbranch_vccnz .LBB0_597
	s_barrier
	s_branch .LBB0_597

.LBB0_736:
	s_or_b64 exec, exec, s[4:5]
	s_waitcnt lgkmcnt(0)
	ds_read_b128 v[32:35], v172 offset:128
	ds_read_b128 v[36:39], v172 offset:160
	s_lshl_b64 s[4:5], s[10:11], 10
	s_add_u32 s4, s38, s4
	s_addc_u32 s5, s39, s5
	s_waitcnt lgkmcnt(1)
	v_rcp_f32_e32 v40, v32
	v_rcp_f32_e32 v41, v33
	s_lshl_b32 s6, s53, 12
	s_add_i32 s6, s6, 0
	s_add_i32 s6, s6, 0x14800
	v_lshlrev_b32_e32 v48, 1, v143
	v_mul_f32_e32 v0, v0, v40
	v_add3_u32 v48, s6, v163, v48
	v_cvt_pk_bf16_f32 v0, v0, s0
	v_rcp_f32_e32 v42, v34
	v_rcp_f32_e32 v43, v35
	s_waitcnt lgkmcnt(0)
	v_rcp_f32_e32 v44, v36
	ds_read_b128 v[32:35], v172 offset:192
	v_rcp_f32_e32 v45, v37
	v_rcp_f32_e32 v46, v38
	v_rcp_f32_e32 v47, v39
	ds_read_b128 v[36:39], v172 offset:224
	ds_write_b16 v48, v0 offset:64
	v_mul_f32_e32 v0, v17, v41
	v_cvt_pk_bf16_f32 v0, v0, s0
	ds_write_b16 v48, v0 offset:128
	v_mul_f32_e32 v0, v1, v41
	v_cvt_pk_bf16_f32 v0, v0, s0
	ds_write_b16 v48, v0 offset:192
	v_mul_f32_e32 v0, v18, v42
	v_cvt_pk_bf16_f32 v0, v0, s0
	ds_write_b16 v48, v0 offset:256
	v_mul_f32_e32 v0, v2, v42
	v_cvt_pk_bf16_f32 v0, v0, s0
	ds_write_b16 v48, v0 offset:320
	v_mul_f32_e32 v0, v19, v43
	v_cvt_pk_bf16_f32 v0, v0, s0
	ds_write_b16 v48, v0 offset:384
	v_mul_f32_e32 v0, v3, v43
	v_cvt_pk_bf16_f32 v0, v0, s0
	ds_write_b16 v48, v0 offset:448
	v_mul_f32_e32 v0, v20, v44
	v_cvt_pk_bf16_f32 v0, v0, s0
	ds_write_b16 v48, v0 offset:1024
	v_mul_f32_e32 v0, v4, v44
	v_cvt_pk_bf16_f32 v0, v0, s0
	ds_write_b16 v48, v0 offset:1088
	v_mul_f32_e32 v0, v21, v45
	v_cvt_pk_bf16_f32 v0, v0, s0
	ds_write_b16 v48, v0 offset:1152
	v_mul_f32_e32 v0, v5, v45
	v_cvt_pk_bf16_f32 v0, v0, s0
	ds_write_b16 v48, v0 offset:1216
	v_mul_f32_e32 v0, v22, v46
	v_cvt_pk_bf16_f32 v0, v0, s0
	ds_write_b16 v48, v0 offset:1280
	v_mul_f32_e32 v0, v6, v46
	v_cvt_pk_bf16_f32 v0, v0, s0
	s_waitcnt lgkmcnt(13)
	v_rcp_f32_e32 v32, v32
	ds_write_b16 v48, v0 offset:1344
	v_mul_f32_e32 v0, v23, v47
	v_cvt_pk_bf16_f32 v0, v0, s0
	ds_write_b16 v48, v0 offset:1408
	v_mul_f32_e32 v0, v7, v47
	v_cvt_pk_bf16_f32 v0, v0, s0
	v_rcp_f32_e32 v33, v33
	ds_write_b16 v48, v0 offset:1472
	v_mul_f32_e32 v0, v24, v32
	v_cvt_pk_bf16_f32 v0, v0, s0
	ds_write_b16 v48, v0 offset:2048
	v_mul_f32_e32 v0, v8, v32
	v_cvt_pk_bf16_f32 v0, v0, s0
	v_rcp_f32_e32 v34, v34
	ds_write_b16 v48, v0 offset:2112
	v_mul_f32_e32 v0, v25, v33
	v_cvt_pk_bf16_f32 v0, v0, s0
	ds_write_b16 v48, v0 offset:2176
	v_mul_f32_e32 v0, v9, v33
	v_cvt_pk_bf16_f32 v0, v0, s0
	v_rcp_f32_e32 v35, v35
	ds_write_b16 v48, v0 offset:2240
	v_mul_f32_e32 v0, v26, v34
	v_cvt_pk_bf16_f32 v0, v0, s0
	ds_write_b16 v48, v0 offset:2304
	v_mul_f32_e32 v0, v10, v34
	v_cvt_pk_bf16_f32 v0, v0, s0
	s_waitcnt lgkmcnt(14)
	v_rcp_f32_e32 v36, v36
	ds_write_b16 v48, v0 offset:2368
	v_mul_f32_e32 v0, v27, v35
	v_cvt_pk_bf16_f32 v0, v0, s0
	ds_write_b16 v48, v0 offset:2432
	v_mul_f32_e32 v0, v11, v35
	v_cvt_pk_bf16_f32 v0, v0, s0
	v_rcp_f32_e32 v37, v37
	ds_write_b16 v48, v0 offset:2496
	v_mul_f32_e32 v0, v28, v36
	v_cvt_pk_bf16_f32 v0, v0, s0
	ds_write_b16 v48, v0 offset:3072
	v_mul_f32_e32 v0, v12, v36
	v_cvt_pk_bf16_f32 v0, v0, s0
	v_rcp_f32_e32 v38, v38
	ds_write_b16 v48, v0 offset:3136
	v_mul_f32_e32 v0, v29, v37
	v_cvt_pk_bf16_f32 v0, v0, s0
	ds_write_b16 v48, v0 offset:3200
	v_mul_f32_e32 v0, v13, v37
	v_cvt_pk_bf16_f32 v0, v0, s0
	v_rcp_f32_e32 v39, v39
	ds_write_b16 v48, v0 offset:3264
	v_mul_f32_e32 v0, v30, v38
	v_cvt_pk_bf16_f32 v0, v0, s0
	ds_write_b16 v48, v0 offset:3328
	v_mul_f32_e32 v0, v14, v38
	v_cvt_pk_bf16_f32 v0, v0, s0
	ds_write_b16 v48, v0 offset:3392
	v_mul_f32_e32 v0, v31, v39
	v_cvt_pk_bf16_f32 v0, v0, s0
	v_mul_f32_e32 v16, v16, v40
	ds_write_b16 v48, v0 offset:3456
	v_mul_f32_e32 v0, v15, v39
	v_cvt_pk_bf16_f32 v16, v16, s0
	v_cvt_pk_bf16_f32 v0, v0, s0
	v_lshlrev_b32_e32 v136, 1, v142
	ds_write_b16 v48, v16
	ds_write_b16 v48, v0 offset:3520
	v_add_u32_e32 v12, s6, v136
	s_waitcnt lgkmcnt(0)
	v_add_u32_e32 v0, v12, v164
	s_lshl_b32 s7, s54, 1
	ds_read_b128 v[0:3], v0
	v_add_u32_e32 v4, v12, v165
	s_add_u32 s4, s4, s7
	ds_read_b128 v[4:7], v4
	s_addc_u32 s5, s5, 0
	v_lshl_add_u64 v[8:9], s[4:5], 0, v[136:137]
	v_lshlrev_b32_e32 v136, 1, v144
	v_lshl_add_u64 v[10:11], v[8:9], 0, v[136:137]
	v_lshlrev_b32_e32 v136, 1, v146
	s_waitcnt lgkmcnt(1)
	global_store_dwordx4 v[10:11], v[0:3], off nt
	s_nop 1
	v_lshl_add_u64 v[0:1], v[8:9], 0, v[136:137]
	s_waitcnt lgkmcnt(0)
	global_store_dwordx4 v[0:1], v[4:7], off nt
	v_add_u32_e32 v0, v12, v166
	ds_read_b128 v[0:3], v0
	v_add_u32_e32 v4, v12, v167
	ds_read_b128 v[4:7], v4
	v_lshlrev_b32_e32 v136, 1, v148
	v_lshl_add_u64 v[10:11], v[8:9], 0, v[136:137]
	v_lshlrev_b32_e32 v136, 1, v150
	s_waitcnt lgkmcnt(1)
	global_store_dwordx4 v[10:11], v[0:3], off nt
	s_nop 1
	v_lshl_add_u64 v[0:1], v[8:9], 0, v[136:137]
	s_waitcnt lgkmcnt(0)
	global_store_dwordx4 v[0:1], v[4:7], off nt
	s_waitcnt lgkmcnt(0)
	s_barrier

.LBB0_741:
	s_lshl_b32 s10, s6, 5
	s_add_i32 s10, s10, 0x8000
	s_mul_i32 s31, s10, 0x600
	s_mul_hi_u32 s28, s10, 0x600
	s_add_u32 s31, s3, s31
	s_addc_u32 s28, s33, s28
	s_add_u32 s4, s31, s4
	s_addc_u32 s5, s28, s5
	s_and_b32 s28, s29, 0x3fffffc0
	s_lshl_b32 s28, s28, 2
	s_add_i32 s28, s28, 0
	s_add_i32 s28, s28, 0x14000
	s_lshl_b32 s31, s7, 7
	s_add_u32 s34, s94, s31
	s_addc_u32 s35, s95, 0
	s_lshl_b32 s31, s6, 4
	s_lshr_b32 s29, s29, 3
	v_and_or_b32 v0, s31, 48, v147
	s_and_b32 s29, s29, 0x1fffffe0
	v_lshl_add_u32 v0, v0, 9, s29
	v_or_b32_e32 v0, v0, v149
	s_cmp_lg_u32 0, -1
	v_lshlrev_b32_e32 v136, 1, v0
	s_cselect_b32 s29, 0, 0
	v_lshl_add_u64 v[0:1], s[34:35], 0, v[136:137]
	s_add_i32 s29, s29, s30
	v_lshl_add_u64 v[0:1], v[0:1], 0, s[14:15]
	s_add_i32 s29, s29, 0xc000
	s_mov_b32 s30, m0
	s_mov_b32 m0, s29
	s_nop 0
	global_load_lds_dwordx4 v[0:1], off
	s_mov_b32 m0, s30
	global_load_dwordx4 v[0:3], v169, s[4:5] offset:128
	global_load_dwordx4 v[4:7], v169, s[4:5] offset:160
	v_or_b32_e32 v136, s10, v143
	v_lshlrev_b64 v[8:9], 7, v[136:137]
	v_lshl_add_u64 v[12:13], v[140:141], 0, v[8:9]
	global_load_dwordx4 v[8:11], v169, s[4:5]
	global_load_dwordx4 v[16:19], v[12:13], off
	global_load_dwordx4 v[20:23], v[12:13], off offset:16
	global_load_dwordx4 v[24:27], v[12:13], off offset:32
	global_load_dwordx4 v[28:31], v[12:13], off offset:48
	global_load_dwordx4 v[60:63], v169, s[4:5] offset:32
	global_load_dwordx4 v[66:69], v169, s[4:5] offset:64
	global_load_dwordx4 v[70:73], v169, s[4:5] offset:96
	s_waitcnt vmcnt(0) lgkmcnt(0)
	s_barrier
	ds_read_b128 v[12:15], v151
	ds_read_b128 v[74:77], v151 offset:2048
	ds_read_b128 v[78:81], v151 offset:4096
	ds_read_b128 v[82:85], v151 offset:6144
	ds_read_b128 v[86:89], v151 offset:8192
	ds_read_b128 v[90:93], v151 offset:10240
	ds_read_b64_tr_b16 v[56:57],v161 offset:0
	ds_read_b64_tr_b16 v[58:59],v161 offset:512
	ds_read_b64_tr_b16 v[52:53],v161 offset:1024
	ds_read_b64_tr_b16 v[54:55],v161 offset:1536
	ds_read_b64_tr_b16 v[48:49],v161 offset:2048
	ds_read_b64_tr_b16 v[50:51],v161 offset:2560
	ds_read_b64_tr_b16 v[44:45],v161 offset:3072
	ds_read_b64_tr_b16 v[46:47],v161 offset:3584
	ds_read_b64_tr_b16 v[40:41],v161 offset:4096
	ds_read_b64_tr_b16 v[42:43],v161 offset:4608
	ds_read_b64_tr_b16 v[36:37],v161 offset:5120
	ds_read_b64_tr_b16 v[38:39],v161 offset:5632
	ds_read_b64_tr_b16 v[32:33],v161 offset:6144
	v_lshl_add_u32 v64, v143, 2, s28
	s_waitcnt vmcnt(0)
	v_lshlrev_b32_e32 v34, 16, v0
	v_lshlrev_b32_e32 v94, 16, v4
	v_and_b32_e32 v96, 0xffff0000, v0
	v_and_b32_e32 v98, 0xffff0000, v4
	v_lshlrev_b32_e32 v100, 16, v1
	v_lshlrev_b32_e32 v102, 16, v5
	v_and_b32_e32 v104, 0xffff0000, v1
	v_and_b32_e32 v106, 0xffff0000, v5
	v_lshlrev_b32_e32 v108, 16, v2
	v_lshlrev_b32_e32 v110, 16, v6
	v_and_b32_e32 v112, 0xffff0000, v2
	v_and_b32_e32 v114, 0xffff0000, v6
	v_lshlrev_b32_e32 v116, 16, v3
	v_lshlrev_b32_e32 v118, 16, v7
	v_and_b32_e32 v120, 0xffff0000, v3
	v_and_b32_e32 v122, 0xffff0000, v7
	s_waitcnt lgkmcnt(5)
	v_mfma_f32_32x32x16_bf16 v[0:15], v[12:15], v[8:11], 0
	v_pk_mul_f32 v[94:95], v[16:17], v[94:95] op_sel:[1,0] op_sel_hi:[0,0]
	v_pk_mul_f32 v[98:99], v[18:19], v[98:99] op_sel:[1,0] op_sel_hi:[0,0]
	v_pk_mul_f32 v[102:103], v[20:21], v[102:103] op_sel:[1,0] op_sel_hi:[0,0]
	v_pk_mul_f32 v[106:107], v[22:23], v[106:107] op_sel:[1,0] op_sel_hi:[0,0]
	v_pk_mul_f32 v[110:111], v[24:25], v[110:111] op_sel:[1,0] op_sel_hi:[0,0]
	v_pk_mul_f32 v[114:115], v[26:27], v[114:115] op_sel:[1,0] op_sel_hi:[0,0]
	v_pk_mul_f32 v[118:119], v[28:29], v[118:119] op_sel:[1,0] op_sel_hi:[0,0]
	s_waitcnt lgkmcnt(4)
	v_mfma_f32_32x32x16_bf16 v[0:15], v[74:77], v[60:63], v[0:15]
	v_pk_mul_f32 v[122:123], v[30:31], v[122:123] op_sel:[1,0] op_sel_hi:[0,0]
	v_pk_fma_f32 v[124:125], v[16:17], v[34:35], v[94:95] neg_lo:[0,0,1] neg_hi:[0,0,1]
	v_pk_fma_f32 v[16:17], v[16:17], v[34:35], v[94:95] op_sel_hi:[1,0,1]
	v_pk_fma_f32 v[34:35], v[18:19], v[96:97], v[98:99] neg_lo:[0,0,1] neg_hi:[0,0,1]
	v_pk_fma_f32 v[18:19], v[18:19], v[96:97], v[98:99] op_sel_hi:[1,0,1]
	v_pk_fma_f32 v[94:95], v[20:21], v[100:101], v[102:103] neg_lo:[0,0,1] neg_hi:[0,0,1]
	v_pk_fma_f32 v[20:21], v[20:21], v[100:101], v[102:103] op_sel_hi:[1,0,1]
	s_waitcnt lgkmcnt(3)
	v_mfma_f32_32x32x16_bf16 v[0:15], v[78:81], v[66:69], v[0:15]
	v_fma_f32 v96, v22, v104, -v106
	v_fma_f32 v97, v23, v105, -v107
	v_fma_f32 v22, v22, v104, v106
	v_fma_f32 v23, v23, v104, v107
	v_fma_f32 v60, v24, v108, -v110
	v_fma_f32 v61, v25, v109, -v111
	v_pk_fma_f32 v[24:25], v[24:25], v[108:109], v[110:111] op_sel_hi:[1,0,1]
	v_pk_fma_f32 v[62:63], v[26:27], v[112:113], v[114:115] neg_lo:[0,0,1] neg_hi:[0,0,1]
	v_pk_fma_f32 v[26:27], v[26:27], v[112:113], v[114:115] op_sel_hi:[1,0,1]
	v_pk_fma_f32 v[74:75], v[28:29], v[116:117], v[118:119] neg_lo:[0,0,1] neg_hi:[0,0,1]
	s_waitcnt lgkmcnt(2)
	v_mfma_f32_32x32x16_bf16 v[0:15], v[82:85], v[70:73], v[0:15]
	v_fma_f32 v28, v28, v116, v118
	v_fma_f32 v29, v29, v116, v119
	v_fma_f32 v66, v30, v120, -v122
	v_fma_f32 v67, v31, v121, -v123
	v_fma_f32 v30, v30, v120, v122
	v_fma_f32 v31, v31, v120, v123
	v_cvt_pk_bf16_f32 v20, v124, v17
	v_cvt_pk_bf16_f32 v22, v34, v19
	v_cvt_pk_bf16_f32 v21, v94, v21
	v_cvt_pk_bf16_f32 v23, v96, v23
	v_cvt_pk_bf16_f32 v24, v60, v25
	v_cvt_pk_bf16_f32 v25, v62, v27
	v_cvt_pk_bf16_f32 v26, v74, v29
	v_cvt_pk_bf16_f32 v27, v66, v31
	v_perm_b32 v16, v22, v20, s48
	v_perm_b32 v17, v23, v21, s48
	v_perm_b32 v18, v25, v24, s48
	v_perm_b32 v19, v27, v26, s48
	ds_read_b64_tr_b16 v[34:35],v161 offset:6656
	ds_read_b64_tr_b16 v[60:61],v161 offset:7168
	ds_read_b64_tr_b16 v[62:63],v161 offset:7680
	s_waitcnt lgkmcnt(1)
	s_nop 0
	v_mfma_f32_32x32x16_bf16 v[0:15], v[86:89], v[16:19], v[0:15]
	v_perm_b32 v16, v22, v20, s49
	v_perm_b32 v17, v23, v21, s49
	v_perm_b32 v18, v25, v24, s49
	v_perm_b32 v19, v27, v26, s49
	s_waitcnt lgkmcnt(0)
	s_nop 0
	v_mfma_f32_32x32x16_bf16 v[0:15], v[90:93], v[16:19], v[0:15]
	v_max3_f32 v8, v0, v1, v168
	v_max3_f32 v9, v2, v3, v168
	s_nop 0
	v_max3_f32 v8, v8, v168, v168
	v_max3_f32 v9, v9, v6, v7
	s_nop 0
	v_max3_f32 v8, v8, v4, v5
	v_max3_f32 v9, v9, v168, v168
	s_nop 0
	v_max3_f32 v8, v8, v168, v168
	v_max3_f32 v9, v9, v168, v168
	s_nop 0
	v_max3_f32 v8, v8, v168, v168
	v_max3_f32 v9, v9, v168, v168
	s_nop 0
	v_max3_f32 v8, v8, v168, v168
	v_max3_f32 v9, v9, v168, v168
	s_nop 0
	v_max3_f32 v8, v8, v168, v168
	v_max3_f32 v9, v9, v168, v168
	s_nop 0
	v_max3_f32 v8, v8, v168, v168
	s_nop 0
	v_max_f32_e32 v8, v8, v9
	s_nop 3
	v_mov_b32_e32 v9, v8
	s_nop 1
	v_permlane32_swap_b32_e32 v8, v9
	v_max_f32_e32 v8, v8, v9
	s_and_saveexec_b64 s[4:5], s[0:1]
	ds_write_b32 v64, v137
	s_or_b64 exec, exec, s[4:5]
	v_sub_f32_e32 v24, v0, v8
	v_sub_f32_e32 v26, v1, v8
	v_sub_f32_e32 v27, v2, v8
	v_sub_f32_e32 v28, v3, v8
	v_sub_f32_e32 v29, v4, v8
	v_sub_f32_e32 v30, v5, v8
	v_sub_f32_e32 v31, v6, v8
	v_sub_f32_e32 v66, v7, v8
	v_exp_f32_e32 v74, v24
	v_exp_f32_e32 v76, v26
	v_exp_f32_e32 v77, v27
	v_exp_f32_e32 v78, v28
	v_exp_f32_e32 v79, v29
	v_exp_f32_e32 v80, v30
	v_exp_f32_e32 v81, v31
	v_exp_f32_e32 v82, v66
	s_waitcnt lgkmcnt(0)
	v_add_u32_e32 v65, s28, v162
	ds_read_b128 v[0:3], v65 offset:64
	ds_read_b128 v[12:15], v65 offset:96
	ds_read_b128 v[16:19], v65
	ds_read_b128 v[20:23], v65 offset:32
	v_cvt_pk_bf16_f32 v66, v74, v76
	v_cvt_pk_bf16_f32 v67, v77, v78
	v_cvt_pk_bf16_f32 v68, v79, v80
	v_cvt_pk_bf16_f32 v69, v81, v82
	v_sub_f32_e32 v25, 0xf149f2ca, v8
	v_exp_f32_e32 v75, v25
	s_waitcnt lgkmcnt(2)
	v_pk_mul_f32 v[14:15], v[14:15], 0 op_sel_hi:[1,0]
	v_pk_mul_f32 v[10:11], v[2:3], 0 op_sel_hi:[1,0]
	s_waitcnt lgkmcnt(0)
	v_pk_mul_f32 v[6:7], v[22:23], 0 op_sel_hi:[1,0]
	v_pk_mul_f32 v[2:3], v[18:19], 0 op_sel_hi:[1,0]
	v_pk_mul_f32 v[12:13], v[12:13], 0 op_sel_hi:[1,0]
	v_pk_mul_f32 v[8:9], v[0:1], 0 op_sel_hi:[1,0]
	v_pk_mul_f32 v[4:5], v[20:21], 0 op_sel_hi:[1,0]
	v_pk_mul_f32 v[0:1], v[16:17], 0 op_sel_hi:[1,0]
	s_waitcnt lgkmcnt(0)
	v_cvt_pk_bf16_f32 v70, v75, v75
	v_mov_b32_e32 v71, v70
	v_mfma_f32_32x32x16_bf16 v[16:31], v[66:69], v[56:59], v[0:15]
	v_mov_b32_e32 v72, v70
	v_mov_b32_e32 v73, v70
	s_lshl_b32 s7, s7, 6
	s_nop 0
	v_mfma_f32_32x32x16_bf16 v[16:31], v[70:73], v[52:55], v[16:31]
	v_mfma_f32_32x32x16_bf16 v[0:15], v[66:69], v[40:43], v[0:15]
	v_add_f32_e32 v41, v77, v75
	v_mfma_f32_32x32x16_bf16 v[16:31], v[70:73], v[48:51], v[16:31]
	v_mfma_f32_32x32x16_bf16 v[0:15], v[70:73], v[36:39], v[0:15]
	v_add_f32_e32 v36, v80, v75
	v_add_f32_e32 v37, v81, v75
	v_mfma_f32_32x32x16_bf16 v[16:31], v[70:73], v[44:47], v[16:31]
	v_add_f32_e32 v44, v74, v75
	v_add_f32_e32 v44, 0, v44
	v_add_f32_e32 v45, v76, v75
	v_add_f32_e32 v40, v45, v44
	v_add_f32_e32 v40, v41, v40
	v_add_f32_e32 v41, v78, v75
	v_add_f32_e32 v40, v41, v40
	v_add_f32_e32 v41, v79, v75
	v_mfma_f32_32x32x16_bf16 v[0:15], v[70:73], v[32:35], v[0:15]
	v_add_f32_e32 v40, v41, v40
	v_add_f32_e32 v36, v36, v40
	v_add_f32_e32 v36, v37, v36
	v_add_f32_e32 v37, v82, v75
	v_add_f32_e32 v36, v37, v36
	v_fmac_f32_e32 v36, 2.0, v75
	v_fmac_f32_e32 v36, 2.0, v75
	v_fmac_f32_e32 v36, 2.0, v75
	v_fmac_f32_e32 v36, 2.0, v75
	v_mfma_f32_32x32x16_bf16 v[0:15], v[70:73], v[60:63], v[0:15]
	v_fmac_f32_e32 v36, 2.0, v75
	v_fmac_f32_e32 v36, 2.0, v75
	v_fmac_f32_e32 v36, 2.0, v75
	v_fmac_f32_e32 v36, 2.0, v75
	v_add_f32_e32 v32, 0, v36
	v_mov_b32_e32 v33, v32
	s_nop 1
	v_permlane32_swap_b32_e32 v32, v33
	s_and_saveexec_b64 s[4:5], s[0:1]
	v_add_f32_e32 v32, v32, v33
	ds_write_b32 v64, v32 offset:128
	s_or_b64 exec, exec, s[4:5]
	s_waitcnt lgkmcnt(0)
	ds_read_b128 v[32:35], v65 offset:128
	ds_read_b128 v[36:39], v65 offset:160
	s_lshl_b64 s[4:5], s[10:11], 10
	s_add_u32 s4, s38, s4
	s_addc_u32 s5, s39, s5
	s_waitcnt lgkmcnt(1)
	v_rcp_f32_e32 v40, v32
	v_rcp_f32_e32 v41, v33
	s_lshl_b32 s6, s6, 12
	s_add_i32 s6, s6, 0
	s_add_i32 s6, s6, 0x14800
	v_lshlrev_b32_e32 v48, 1, v143
	v_mul_f32_e32 v0, v0, v40
	v_add3_u32 v48, s6, v163, v48
	v_cvt_pk_bf16_f32 v0, v0, s0
	v_rcp_f32_e32 v42, v34
	v_rcp_f32_e32 v43, v35
	s_waitcnt lgkmcnt(0)
	v_rcp_f32_e32 v44, v36
	ds_read_b128 v[32:35], v65 offset:192
	v_rcp_f32_e32 v45, v37
	v_rcp_f32_e32 v46, v38
	v_rcp_f32_e32 v47, v39
	ds_read_b128 v[36:39], v65 offset:224
	ds_write_b16 v48, v0 offset:64
	v_mul_f32_e32 v0, v17, v41
	v_cvt_pk_bf16_f32 v0, v0, s0
	ds_write_b16 v48, v0 offset:128
	v_mul_f32_e32 v0, v1, v41
	v_cvt_pk_bf16_f32 v0, v0, s0
	ds_write_b16 v48, v0 offset:192
	v_mul_f32_e32 v0, v18, v42
	v_cvt_pk_bf16_f32 v0, v0, s0
	ds_write_b16 v48, v0 offset:256
	v_mul_f32_e32 v0, v2, v42
	v_cvt_pk_bf16_f32 v0, v0, s0
	ds_write_b16 v48, v0 offset:320
	v_mul_f32_e32 v0, v19, v43
	v_cvt_pk_bf16_f32 v0, v0, s0
	ds_write_b16 v48, v0 offset:384
	v_mul_f32_e32 v0, v3, v43
	v_cvt_pk_bf16_f32 v0, v0, s0
	ds_write_b16 v48, v0 offset:448
	v_mul_f32_e32 v0, v20, v44
	v_cvt_pk_bf16_f32 v0, v0, s0
	ds_write_b16 v48, v0 offset:1024
	v_mul_f32_e32 v0, v4, v44
	v_cvt_pk_bf16_f32 v0, v0, s0
	ds_write_b16 v48, v0 offset:1088
	v_mul_f32_e32 v0, v21, v45
	v_cvt_pk_bf16_f32 v0, v0, s0
	ds_write_b16 v48, v0 offset:1152
	v_mul_f32_e32 v0, v5, v45
	v_cvt_pk_bf16_f32 v0, v0, s0
	ds_write_b16 v48, v0 offset:1216
	v_mul_f32_e32 v0, v22, v46
	v_cvt_pk_bf16_f32 v0, v0, s0
	ds_write_b16 v48, v0 offset:1280
	v_mul_f32_e32 v0, v6, v46
	v_cvt_pk_bf16_f32 v0, v0, s0
	s_waitcnt lgkmcnt(13)
	v_rcp_f32_e32 v32, v32
	ds_write_b16 v48, v0 offset:1344
	v_mul_f32_e32 v0, v23, v47
	v_cvt_pk_bf16_f32 v0, v0, s0
	ds_write_b16 v48, v0 offset:1408
	v_mul_f32_e32 v0, v7, v47
	v_cvt_pk_bf16_f32 v0, v0, s0
	v_rcp_f32_e32 v33, v33
	ds_write_b16 v48, v0 offset:1472
	v_mul_f32_e32 v0, v24, v32
	v_cvt_pk_bf16_f32 v0, v0, s0
	ds_write_b16 v48, v0 offset:2048
	v_mul_f32_e32 v0, v8, v32
	v_cvt_pk_bf16_f32 v0, v0, s0
	v_rcp_f32_e32 v34, v34
	ds_write_b16 v48, v0 offset:2112
	v_mul_f32_e32 v0, v25, v33
	v_cvt_pk_bf16_f32 v0, v0, s0
	ds_write_b16 v48, v0 offset:2176
	v_mul_f32_e32 v0, v9, v33
	v_cvt_pk_bf16_f32 v0, v0, s0
	v_rcp_f32_e32 v35, v35
	ds_write_b16 v48, v0 offset:2240
	v_mul_f32_e32 v0, v26, v34
	v_cvt_pk_bf16_f32 v0, v0, s0
	ds_write_b16 v48, v0 offset:2304
	v_mul_f32_e32 v0, v10, v34
	v_cvt_pk_bf16_f32 v0, v0, s0
	s_waitcnt lgkmcnt(14)
	v_rcp_f32_e32 v36, v36
	ds_write_b16 v48, v0 offset:2368
	v_mul_f32_e32 v0, v27, v35
	v_cvt_pk_bf16_f32 v0, v0, s0
	ds_write_b16 v48, v0 offset:2432
	v_mul_f32_e32 v0, v11, v35
	v_cvt_pk_bf16_f32 v0, v0, s0
	v_rcp_f32_e32 v37, v37
	ds_write_b16 v48, v0 offset:2496
	v_mul_f32_e32 v0, v28, v36
	v_cvt_pk_bf16_f32 v0, v0, s0
	ds_write_b16 v48, v0 offset:3072
	v_mul_f32_e32 v0, v12, v36
	v_cvt_pk_bf16_f32 v0, v0, s0
	v_rcp_f32_e32 v38, v38
	ds_write_b16 v48, v0 offset:3136
	v_mul_f32_e32 v0, v29, v37
	v_cvt_pk_bf16_f32 v0, v0, s0
	ds_write_b16 v48, v0 offset:3200
	v_mul_f32_e32 v0, v13, v37
	v_cvt_pk_bf16_f32 v0, v0, s0
	v_rcp_f32_e32 v39, v39
	ds_write_b16 v48, v0 offset:3264
	v_mul_f32_e32 v0, v30, v38
	v_cvt_pk_bf16_f32 v0, v0, s0
	ds_write_b16 v48, v0 offset:3328
	v_mul_f32_e32 v0, v14, v38
	v_cvt_pk_bf16_f32 v0, v0, s0
	ds_write_b16 v48, v0 offset:3392
	v_mul_f32_e32 v0, v31, v39
	v_cvt_pk_bf16_f32 v0, v0, s0
	v_mul_f32_e32 v16, v16, v40
	ds_write_b16 v48, v0 offset:3456
	v_mul_f32_e32 v0, v15, v39
	v_cvt_pk_bf16_f32 v16, v16, s0
	v_cvt_pk_bf16_f32 v0, v0, s0
	v_lshlrev_b32_e32 v136, 1, v142
	ds_write_b16 v48, v16
	ds_write_b16 v48, v0 offset:3520
	v_add_u32_e32 v12, s6, v136
	s_waitcnt lgkmcnt(0)
	v_add_u32_e32 v0, v12, v164
	s_lshl_b32 s7, s7, 1
	ds_read_b128 v[0:3], v0
	v_add_u32_e32 v4, v12, v165
	s_add_u32 s4, s4, s7
	ds_read_b128 v[4:7], v4
	s_addc_u32 s5, s5, 0
	v_lshl_add_u64 v[8:9], s[4:5], 0, v[136:137]
	v_lshlrev_b32_e32 v136, 1, v144
	v_lshl_add_u64 v[10:11], v[8:9], 0, v[136:137]
	v_lshlrev_b32_e32 v136, 1, v146
	s_waitcnt lgkmcnt(1)
	global_store_dwordx4 v[10:11], v[0:3], off nt
	s_nop 1
	v_lshl_add_u64 v[0:1], v[8:9], 0, v[136:137]
	s_waitcnt lgkmcnt(0)
	global_store_dwordx4 v[0:1], v[4:7], off nt
	v_add_u32_e32 v0, v12, v166
	ds_read_b128 v[0:3], v0
	v_add_u32_e32 v4, v12, v167
	ds_read_b128 v[4:7], v4
	v_lshlrev_b32_e32 v136, 1, v148
	v_lshl_add_u64 v[10:11], v[8:9], 0, v[136:137]
	v_lshlrev_b32_e32 v136, 1, v150
	s_waitcnt lgkmcnt(1)
	global_store_dwordx4 v[10:11], v[0:3], off nt
	s_nop 1
	v_lshl_add_u64 v[0:1], v[8:9], 0, v[136:137]
	s_waitcnt lgkmcnt(0)
	global_store_dwordx4 v[0:1], v[4:7], off nt
	s_waitcnt lgkmcnt(0)
	s_barrier
	s_branch .LBB0_737
